# w_out/down GEMM epilogue: store addresses as SGPR base + 32-bit row-pair offset + immediate instead of a 64-bit VALU chain per element
# baseline (speedup 1.0000x reference)
.Lg2_loop:
	ds_read_b128 v[148:151], v117
	ds_read_b128 v[152:155], v117 offset:4096
	ds_read_b128 v[156:159], v121 offset:32768
	ds_read_b128 v[160:163], v121 offset:40960
	s_waitcnt lgkmcnt(4)
	v_mfma_f32_32x32x16_bf16 v[50:65], v[132:135], v[140:143], v[50:65]
	s_add_u32 m0, s37, 0x4000
	s_nop 0
	global_load_lds_dwordx4 v[70:71], off
	v_lshl_add_u64 v[70:71], v[70:71], 0, s[98:99]
	v_mfma_f32_32x32x16_bf16 v[34:49], v[132:135], v[144:147], v[34:49]
	s_add_u32 m0, s37, 0xc000
	s_nop 0
	global_load_lds_dwordx4 v[78:79], off
	v_lshl_add_u64 v[78:79], v[78:79], 0, s[98:99]
	v_mfma_f32_32x32x16_bf16 v[18:33], v[136:139], v[140:143], v[18:33]
	s_add_u32 m0, s37, 0x5000
	s_nop 0
	global_load_lds_dwordx4 v[72:73], off
	v_lshl_add_u64 v[72:73], v[72:73], 0, s[98:99]
	v_mfma_f32_32x32x16_bf16 v[2:17], v[136:139], v[144:147], v[2:17]
	ds_read_b128 v[132:135], v118
	ds_read_b128 v[136:139], v118 offset:4096
	ds_read_b128 v[140:143], v122 offset:32768
	ds_read_b128 v[144:147], v122 offset:40960
	s_waitcnt lgkmcnt(4)
	v_mfma_f32_32x32x16_bf16 v[50:65], v[148:151], v[156:159], v[50:65]
	s_add_u32 m0, s37, 0xd000
	s_nop 0
	global_load_lds_dwordx4 v[80:81], off
	v_lshl_add_u64 v[80:81], v[80:81], 0, s[98:99]
	v_mfma_f32_32x32x16_bf16 v[34:49], v[148:151], v[160:163], v[34:49]
	s_add_u32 m0, s37, 0x6000
	s_nop 0
	global_load_lds_dwordx4 v[74:75], off
	v_lshl_add_u64 v[74:75], v[74:75], 0, s[98:99]
	v_mfma_f32_32x32x16_bf16 v[18:33], v[152:155], v[156:159], v[18:33]
	s_add_u32 m0, s37, 0xe000
	s_nop 0
	global_load_lds_dwordx4 v[82:83], off
	v_lshl_add_u64 v[82:83], v[82:83], 0, s[98:99]
	v_mfma_f32_32x32x16_bf16 v[2:17], v[152:155], v[160:163], v[2:17]
	ds_read_b128 v[148:151], v119
	ds_read_b128 v[152:155], v119 offset:4096
	ds_read_b128 v[156:159], v123 offset:32768
	ds_read_b128 v[160:163], v123 offset:40960
	s_waitcnt lgkmcnt(4)
	v_mfma_f32_32x32x16_bf16 v[50:65], v[132:135], v[140:143], v[50:65]
	s_add_u32 m0, s37, 0x7000
	s_nop 0
	global_load_lds_dwordx4 v[76:77], off
	v_lshl_add_u64 v[76:77], v[76:77], 0, s[98:99]
	v_mfma_f32_32x32x16_bf16 v[34:49], v[132:135], v[144:147], v[34:49]
	s_add_u32 m0, s37, 0xf000
	s_nop 0
	global_load_lds_dwordx4 v[84:85], off
	v_lshl_add_u64 v[84:85], v[84:85], 0, s[98:99]
	v_mfma_f32_32x32x16_bf16 v[18:33], v[136:139], v[140:143], v[18:33]
	v_mfma_f32_32x32x16_bf16 v[2:17], v[136:139], v[144:147], v[2:17]
	s_waitcnt vmcnt(0) lgkmcnt(0)
	s_barrier
	ds_read_b128 v[132:135], v116 offset:16384
	ds_read_b128 v[136:139], v116 offset:20480
	ds_read_b128 v[140:143], v120 offset:49152
	ds_read_b128 v[144:147], v120 offset:57344
	v_mfma_f32_32x32x16_bf16 v[50:65], v[148:151], v[156:159], v[50:65]
	v_mfma_f32_32x32x16_bf16 v[34:49], v[148:151], v[160:163], v[34:49]
	v_mfma_f32_32x32x16_bf16 v[18:33], v[152:155], v[156:159], v[18:33]
	v_mfma_f32_32x32x16_bf16 v[2:17], v[152:155], v[160:163], v[2:17]
	ds_read_b128 v[148:151], v117 offset:16384
	ds_read_b128 v[152:155], v117 offset:20480
	ds_read_b128 v[156:159], v121 offset:49152
	ds_read_b128 v[160:163], v121 offset:57344
	s_waitcnt lgkmcnt(4)
	v_mfma_f32_32x32x16_bf16 v[50:65], v[132:135], v[140:143], v[50:65]
	s_mov_b32 m0, s37
	s_nop 0
	global_load_lds_dwordx4 v[70:71], off
	v_lshl_add_u64 v[70:71], v[70:71], 0, s[98:99]
	v_mfma_f32_32x32x16_bf16 v[34:49], v[132:135], v[144:147], v[34:49]
	s_add_u32 m0, s37, 0x8000
	s_nop 0
	global_load_lds_dwordx4 v[78:79], off
	v_lshl_add_u64 v[78:79], v[78:79], 0, s[98:99]
	v_mfma_f32_32x32x16_bf16 v[18:33], v[136:139], v[140:143], v[18:33]
	s_add_u32 m0, s37, 0x1000
	s_nop 0
	global_load_lds_dwordx4 v[72:73], off
	v_lshl_add_u64 v[72:73], v[72:73], 0, s[98:99]
	v_mfma_f32_32x32x16_bf16 v[2:17], v[136:139], v[144:147], v[2:17]
	ds_read_b128 v[132:135], v118 offset:16384
	ds_read_b128 v[136:139], v118 offset:20480
	ds_read_b128 v[140:143], v122 offset:49152
	ds_read_b128 v[144:147], v122 offset:57344
	s_waitcnt lgkmcnt(4)
	v_mfma_f32_32x32x16_bf16 v[50:65], v[148:151], v[156:159], v[50:65]
	s_add_u32 m0, s37, 0x9000
	s_nop 0
	global_load_lds_dwordx4 v[80:81], off
	v_lshl_add_u64 v[80:81], v[80:81], 0, s[98:99]
	v_mfma_f32_32x32x16_bf16 v[34:49], v[148:151], v[160:163], v[34:49]
	s_add_u32 m0, s37, 0x2000
	s_nop 0
	global_load_lds_dwordx4 v[74:75], off
	v_lshl_add_u64 v[74:75], v[74:75], 0, s[98:99]
	v_mfma_f32_32x32x16_bf16 v[18:33], v[152:155], v[156:159], v[18:33]
	s_add_u32 m0, s37, 0xa000
	s_nop 0
	global_load_lds_dwordx4 v[82:83], off
	v_lshl_add_u64 v[82:83], v[82:83], 0, s[98:99]
	v_mfma_f32_32x32x16_bf16 v[2:17], v[152:155], v[160:163], v[2:17]
	ds_read_b128 v[148:151], v119 offset:16384
	ds_read_b128 v[152:155], v119 offset:20480
	ds_read_b128 v[156:159], v123 offset:49152
	ds_read_b128 v[160:163], v123 offset:57344
	s_waitcnt lgkmcnt(4)
	v_mfma_f32_32x32x16_bf16 v[50:65], v[132:135], v[140:143], v[50:65]
	s_add_u32 m0, s37, 0x3000
	s_nop 0
	global_load_lds_dwordx4 v[76:77], off
	v_lshl_add_u64 v[76:77], v[76:77], 0, s[98:99]
	v_mfma_f32_32x32x16_bf16 v[34:49], v[132:135], v[144:147], v[34:49]
	s_add_u32 m0, s37, 0xb000
	s_nop 0
	global_load_lds_dwordx4 v[84:85], off
	v_lshl_add_u64 v[84:85], v[84:85], 0, s[98:99]
	v_mfma_f32_32x32x16_bf16 v[18:33], v[136:139], v[140:143], v[18:33]
	v_mfma_f32_32x32x16_bf16 v[2:17], v[136:139], v[144:147], v[2:17]
	s_waitcnt vmcnt(0) lgkmcnt(0)
	s_barrier
	ds_read_b128 v[132:135], v116
	ds_read_b128 v[136:139], v116 offset:4096
	ds_read_b128 v[140:143], v120 offset:32768
	ds_read_b128 v[144:147], v120 offset:40960
	v_mfma_f32_32x32x16_bf16 v[50:65], v[148:151], v[156:159], v[50:65]
	v_mfma_f32_32x32x16_bf16 v[34:49], v[148:151], v[160:163], v[34:49]
	v_mfma_f32_32x32x16_bf16 v[18:33], v[152:155], v[156:159], v[18:33]
	v_mfma_f32_32x32x16_bf16 v[2:17], v[152:155], v[160:163], v[2:17]
	s_sub_u32 s39, s39, 1
	s_cmp_lg_u32 s39, 0
	s_cbranch_scc1 .Lg2_loop
	ds_read_b128 v[148:151], v117
	ds_read_b128 v[152:155], v117 offset:4096
	ds_read_b128 v[156:159], v121 offset:32768
	ds_read_b128 v[160:163], v121 offset:40960
	s_waitcnt lgkmcnt(4)
	v_mfma_f32_32x32x16_bf16 v[50:65], v[132:135], v[140:143], v[50:65]
	s_add_u32 m0, s37, 0x4000
	s_nop 0
	global_load_lds_dwordx4 v[70:71], off
	v_lshl_add_u64 v[70:71], v[70:71], 0, s[98:99]
	v_mfma_f32_32x32x16_bf16 v[34:49], v[132:135], v[144:147], v[34:49]
	s_add_u32 m0, s37, 0xc000
	s_nop 0
	global_load_lds_dwordx4 v[78:79], off
	v_lshl_add_u64 v[78:79], v[78:79], 0, s[98:99]
	v_mfma_f32_32x32x16_bf16 v[18:33], v[136:139], v[140:143], v[18:33]
	s_add_u32 m0, s37, 0x5000
	s_nop 0
	global_load_lds_dwordx4 v[72:73], off
	v_lshl_add_u64 v[72:73], v[72:73], 0, s[98:99]
	v_mfma_f32_32x32x16_bf16 v[2:17], v[136:139], v[144:147], v[2:17]
	ds_read_b128 v[132:135], v118
	ds_read_b128 v[136:139], v118 offset:4096
	ds_read_b128 v[140:143], v122 offset:32768
	ds_read_b128 v[144:147], v122 offset:40960
	s_waitcnt lgkmcnt(4)
	v_mfma_f32_32x32x16_bf16 v[50:65], v[148:151], v[156:159], v[50:65]
	s_add_u32 m0, s37, 0xd000
	s_nop 0
	global_load_lds_dwordx4 v[80:81], off
	v_lshl_add_u64 v[80:81], v[80:81], 0, s[98:99]
	v_mfma_f32_32x32x16_bf16 v[34:49], v[148:151], v[160:163], v[34:49]
	s_add_u32 m0, s37, 0x6000
	s_nop 0
	global_load_lds_dwordx4 v[74:75], off
	v_lshl_add_u64 v[74:75], v[74:75], 0, s[98:99]
	v_mfma_f32_32x32x16_bf16 v[18:33], v[152:155], v[156:159], v[18:33]
	s_add_u32 m0, s37, 0xe000
	s_nop 0
	global_load_lds_dwordx4 v[82:83], off
	v_lshl_add_u64 v[82:83], v[82:83], 0, s[98:99]
	v_mfma_f32_32x32x16_bf16 v[2:17], v[152:155], v[160:163], v[2:17]
	ds_read_b128 v[148:151], v119
	ds_read_b128 v[152:155], v119 offset:4096
	ds_read_b128 v[156:159], v123 offset:32768
	ds_read_b128 v[160:163], v123 offset:40960
	s_waitcnt lgkmcnt(4)
	v_mfma_f32_32x32x16_bf16 v[50:65], v[132:135], v[140:143], v[50:65]
	s_add_u32 m0, s37, 0x7000
	s_nop 0
	global_load_lds_dwordx4 v[76:77], off
	v_lshl_add_u64 v[76:77], v[76:77], 0, s[98:99]
	v_mfma_f32_32x32x16_bf16 v[34:49], v[132:135], v[144:147], v[34:49]
	s_add_u32 m0, s37, 0xf000
	s_nop 0
	global_load_lds_dwordx4 v[84:85], off
	v_lshl_add_u64 v[84:85], v[84:85], 0, s[98:99]
	v_mfma_f32_32x32x16_bf16 v[18:33], v[136:139], v[140:143], v[18:33]
	v_mfma_f32_32x32x16_bf16 v[2:17], v[136:139], v[144:147], v[2:17]
	s_waitcnt vmcnt(0) lgkmcnt(0)
	s_barrier
	ds_read_b128 v[132:135], v116 offset:16384
	ds_read_b128 v[136:139], v116 offset:20480
	ds_read_b128 v[140:143], v120 offset:49152
	ds_read_b128 v[144:147], v120 offset:57344
	v_mfma_f32_32x32x16_bf16 v[50:65], v[148:151], v[156:159], v[50:65]
	v_mfma_f32_32x32x16_bf16 v[34:49], v[148:151], v[160:163], v[34:49]
	v_mfma_f32_32x32x16_bf16 v[18:33], v[152:155], v[156:159], v[18:33]
	v_mfma_f32_32x32x16_bf16 v[2:17], v[152:155], v[160:163], v[2:17]
	ds_read_b128 v[148:151], v117 offset:16384
	ds_read_b128 v[152:155], v117 offset:20480
	ds_read_b128 v[156:159], v121 offset:49152
	ds_read_b128 v[160:163], v121 offset:57344
	s_waitcnt lgkmcnt(4)
	v_mfma_f32_32x32x16_bf16 v[50:65], v[132:135], v[140:143], v[50:65]
	v_mfma_f32_32x32x16_bf16 v[34:49], v[132:135], v[144:147], v[34:49]
	v_mfma_f32_32x32x16_bf16 v[18:33], v[136:139], v[140:143], v[18:33]
	v_mfma_f32_32x32x16_bf16 v[2:17], v[136:139], v[144:147], v[2:17]
	ds_read_b128 v[132:135], v118 offset:16384
	ds_read_b128 v[136:139], v118 offset:20480
	ds_read_b128 v[140:143], v122 offset:49152
	ds_read_b128 v[144:147], v122 offset:57344
	s_waitcnt lgkmcnt(4)
	v_mfma_f32_32x32x16_bf16 v[50:65], v[148:151], v[156:159], v[50:65]
	v_mfma_f32_32x32x16_bf16 v[34:49], v[148:151], v[160:163], v[34:49]
	v_mfma_f32_32x32x16_bf16 v[18:33], v[152:155], v[156:159], v[18:33]
	v_mfma_f32_32x32x16_bf16 v[2:17], v[152:155], v[160:163], v[2:17]
	ds_read_b128 v[148:151], v119 offset:16384
	ds_read_b128 v[152:155], v119 offset:20480
	ds_read_b128 v[156:159], v123 offset:49152
	ds_read_b128 v[160:163], v123 offset:57344
	s_waitcnt lgkmcnt(4)
	v_mfma_f32_32x32x16_bf16 v[50:65], v[132:135], v[140:143], v[50:65]
	v_mfma_f32_32x32x16_bf16 v[34:49], v[132:135], v[144:147], v[34:49]
	v_mfma_f32_32x32x16_bf16 v[18:33], v[136:139], v[140:143], v[18:33]
	v_mfma_f32_32x32x16_bf16 v[2:17], v[136:139], v[144:147], v[2:17]
	s_waitcnt vmcnt(0) lgkmcnt(0)
	s_barrier
	v_mfma_f32_32x32x16_bf16 v[50:65], v[148:151], v[156:159], v[50:65]
	v_mfma_f32_32x32x16_bf16 v[34:49], v[148:151], v[160:163], v[34:49]
	v_mfma_f32_32x32x16_bf16 v[18:33], v[152:155], v[156:159], v[18:33]
	v_mfma_f32_32x32x16_bf16 v[2:17], v[152:155], v[160:163], v[2:17]
	v_or_b32_e32 v70, s38, v91
	v_add_u32_e32 v72, s27, v96
	v_readlane_b32 s38, v253, 18
	v_readlane_b32 s39, v253, 19
	s_nop 15
	v_lshlrev_b32_e32 v72, 11, v72
	v_lshl_add_u32 v70, v70, 1, v72
	v_bfe_u32 v73, v50, 16, 1
	v_add3_u32 v73, v50, v73, s26
	global_store_short_d16_hi v70, v73, s[38:39]
	v_bfe_u32 v74, v51, 16, 1
	v_add3_u32 v74, v51, v74, s26
	global_store_short_d16_hi v70, v74, s[38:39] offset:2048
	v_bfe_u32 v75, v34, 16, 1
	v_add3_u32 v75, v34, v75, s26
	global_store_short_d16_hi v70, v75, s[38:39] offset:128
	v_bfe_u32 v76, v35, 16, 1
	v_add3_u32 v76, v35, v76, s26
	global_store_short_d16_hi v70, v76, s[38:39] offset:2176
	v_add_u32_e32 v72, 0x1000, v70
	v_bfe_u32 v77, v52, 16, 1
	v_add3_u32 v77, v52, v77, s26
	global_store_short_d16_hi v72, v77, s[38:39]
	v_bfe_u32 v78, v53, 16, 1
	v_add3_u32 v78, v53, v78, s26
	global_store_short_d16_hi v72, v78, s[38:39] offset:2048
	v_bfe_u32 v79, v36, 16, 1
	v_add3_u32 v79, v36, v79, s26
	global_store_short_d16_hi v72, v79, s[38:39] offset:128
	v_bfe_u32 v80, v37, 16, 1
	v_add3_u32 v80, v37, v80, s26
	global_store_short_d16_hi v72, v80, s[38:39] offset:2176
	v_add_u32_e32 v71, 0x4000, v70
	v_bfe_u32 v73, v54, 16, 1
	v_add3_u32 v73, v54, v73, s26
	global_store_short_d16_hi v71, v73, s[38:39]
	v_bfe_u32 v74, v55, 16, 1
	v_add3_u32 v74, v55, v74, s26
	global_store_short_d16_hi v71, v74, s[38:39] offset:2048
	v_bfe_u32 v75, v38, 16, 1
	v_add3_u32 v75, v38, v75, s26
	global_store_short_d16_hi v71, v75, s[38:39] offset:128
	v_bfe_u32 v76, v39, 16, 1
	v_add3_u32 v76, v39, v76, s26
	global_store_short_d16_hi v71, v76, s[38:39] offset:2176
	v_add_u32_e32 v72, 0x5000, v70
	v_bfe_u32 v77, v56, 16, 1
	v_add3_u32 v77, v56, v77, s26
	global_store_short_d16_hi v72, v77, s[38:39]
	v_bfe_u32 v78, v57, 16, 1
	v_add3_u32 v78, v57, v78, s26
	global_store_short_d16_hi v72, v78, s[38:39] offset:2048
	v_bfe_u32 v79, v40, 16, 1
	v_add3_u32 v79, v40, v79, s26
	global_store_short_d16_hi v72, v79, s[38:39] offset:128
	v_bfe_u32 v80, v41, 16, 1
	v_add3_u32 v80, v41, v80, s26
	global_store_short_d16_hi v72, v80, s[38:39] offset:2176
	v_add_u32_e32 v71, 0x8000, v70
	v_bfe_u32 v73, v58, 16, 1
	v_add3_u32 v73, v58, v73, s26
	global_store_short_d16_hi v71, v73, s[38:39]
	v_bfe_u32 v74, v59, 16, 1
	v_add3_u32 v74, v59, v74, s26
	global_store_short_d16_hi v71, v74, s[38:39] offset:2048
	v_bfe_u32 v75, v42, 16, 1
	v_add3_u32 v75, v42, v75, s26
	global_store_short_d16_hi v71, v75, s[38:39] offset:128
	v_bfe_u32 v76, v43, 16, 1
	v_add3_u32 v76, v43, v76, s26
	global_store_short_d16_hi v71, v76, s[38:39] offset:2176
	v_add_u32_e32 v72, 0x9000, v70
	v_bfe_u32 v77, v60, 16, 1
	v_add3_u32 v77, v60, v77, s26
	global_store_short_d16_hi v72, v77, s[38:39]
	v_bfe_u32 v78, v61, 16, 1
	v_add3_u32 v78, v61, v78, s26
	global_store_short_d16_hi v72, v78, s[38:39] offset:2048
	v_bfe_u32 v79, v44, 16, 1
	v_add3_u32 v79, v44, v79, s26
	global_store_short_d16_hi v72, v79, s[38:39] offset:128
	v_bfe_u32 v80, v45, 16, 1
	v_add3_u32 v80, v45, v80, s26
	global_store_short_d16_hi v72, v80, s[38:39] offset:2176
	v_add_u32_e32 v71, 0xc000, v70
	v_bfe_u32 v73, v62, 16, 1
	v_add3_u32 v73, v62, v73, s26
	global_store_short_d16_hi v71, v73, s[38:39]
	v_bfe_u32 v74, v63, 16, 1
	v_add3_u32 v74, v63, v74, s26
	global_store_short_d16_hi v71, v74, s[38:39] offset:2048
	v_bfe_u32 v75, v46, 16, 1
	v_add3_u32 v75, v46, v75, s26
	global_store_short_d16_hi v71, v75, s[38:39] offset:128
	v_bfe_u32 v76, v47, 16, 1
	v_add3_u32 v76, v47, v76, s26
	global_store_short_d16_hi v71, v76, s[38:39] offset:2176
	v_add_u32_e32 v72, 0xd000, v70
	v_bfe_u32 v77, v64, 16, 1
	v_add3_u32 v77, v64, v77, s26
	global_store_short_d16_hi v72, v77, s[38:39]
	v_bfe_u32 v78, v65, 16, 1
	v_add3_u32 v78, v65, v78, s26
	global_store_short_d16_hi v72, v78, s[38:39] offset:2048
	v_bfe_u32 v79, v48, 16, 1
	v_add3_u32 v79, v48, v79, s26
	global_store_short_d16_hi v72, v79, s[38:39] offset:128
	v_bfe_u32 v80, v49, 16, 1
	v_add3_u32 v80, v49, v80, s26
	global_store_short_d16_hi v72, v80, s[38:39] offset:2176
	v_add_u32_e32 v71, 0x10000, v70
	v_bfe_u32 v73, v18, 16, 1
	v_add3_u32 v73, v18, v73, s26
	global_store_short_d16_hi v71, v73, s[38:39]
	v_bfe_u32 v74, v19, 16, 1
	v_add3_u32 v74, v19, v74, s26
	global_store_short_d16_hi v71, v74, s[38:39] offset:2048
	v_bfe_u32 v75, v2, 16, 1
	v_add3_u32 v75, v2, v75, s26
	global_store_short_d16_hi v71, v75, s[38:39] offset:128
	v_bfe_u32 v76, v3, 16, 1
	v_add3_u32 v76, v3, v76, s26
	global_store_short_d16_hi v71, v76, s[38:39] offset:2176
	v_add_u32_e32 v72, 0x11000, v70
	v_bfe_u32 v77, v20, 16, 1
	v_add3_u32 v77, v20, v77, s26
	global_store_short_d16_hi v72, v77, s[38:39]
	v_bfe_u32 v78, v21, 16, 1
	v_add3_u32 v78, v21, v78, s26
	global_store_short_d16_hi v72, v78, s[38:39] offset:2048
	v_bfe_u32 v79, v4, 16, 1
	v_add3_u32 v79, v4, v79, s26
	global_store_short_d16_hi v72, v79, s[38:39] offset:128
	v_bfe_u32 v80, v5, 16, 1
	v_add3_u32 v80, v5, v80, s26
	global_store_short_d16_hi v72, v80, s[38:39] offset:2176
	v_add_u32_e32 v71, 0x14000, v70
	v_bfe_u32 v73, v22, 16, 1
	v_add3_u32 v73, v22, v73, s26
	global_store_short_d16_hi v71, v73, s[38:39]
	v_bfe_u32 v74, v23, 16, 1
	v_add3_u32 v74, v23, v74, s26
	global_store_short_d16_hi v71, v74, s[38:39] offset:2048
	v_bfe_u32 v75, v6, 16, 1
	v_add3_u32 v75, v6, v75, s26
	global_store_short_d16_hi v71, v75, s[38:39] offset:128
	v_bfe_u32 v76, v7, 16, 1
	v_add3_u32 v76, v7, v76, s26
	global_store_short_d16_hi v71, v76, s[38:39] offset:2176
	v_add_u32_e32 v72, 0x15000, v70
	v_bfe_u32 v77, v24, 16, 1
	v_add3_u32 v77, v24, v77, s26
	global_store_short_d16_hi v72, v77, s[38:39]
	v_bfe_u32 v78, v25, 16, 1
	v_add3_u32 v78, v25, v78, s26
	global_store_short_d16_hi v72, v78, s[38:39] offset:2048
	v_bfe_u32 v79, v8, 16, 1
	v_add3_u32 v79, v8, v79, s26
	global_store_short_d16_hi v72, v79, s[38:39] offset:128
	v_bfe_u32 v80, v9, 16, 1
	v_add3_u32 v80, v9, v80, s26
	global_store_short_d16_hi v72, v80, s[38:39] offset:2176
	v_add_u32_e32 v71, 0x18000, v70
	v_bfe_u32 v73, v26, 16, 1
	v_add3_u32 v73, v26, v73, s26
	global_store_short_d16_hi v71, v73, s[38:39]
	v_bfe_u32 v74, v27, 16, 1
	v_add3_u32 v74, v27, v74, s26
	global_store_short_d16_hi v71, v74, s[38:39] offset:2048
	v_bfe_u32 v75, v10, 16, 1
	v_add3_u32 v75, v10, v75, s26
	global_store_short_d16_hi v71, v75, s[38:39] offset:128
	v_bfe_u32 v76, v11, 16, 1
	v_add3_u32 v76, v11, v76, s26
	global_store_short_d16_hi v71, v76, s[38:39] offset:2176
	v_add_u32_e32 v72, 0x19000, v70
	v_bfe_u32 v77, v28, 16, 1
	v_add3_u32 v77, v28, v77, s26
	global_store_short_d16_hi v72, v77, s[38:39]
	v_bfe_u32 v78, v29, 16, 1
	v_add3_u32 v78, v29, v78, s26
	global_store_short_d16_hi v72, v78, s[38:39] offset:2048
	v_bfe_u32 v79, v12, 16, 1
	v_add3_u32 v79, v12, v79, s26
	global_store_short_d16_hi v72, v79, s[38:39] offset:128
	v_bfe_u32 v80, v13, 16, 1
	v_add3_u32 v80, v13, v80, s26
	global_store_short_d16_hi v72, v80, s[38:39] offset:2176
	v_add_u32_e32 v71, 0x1c000, v70
	v_bfe_u32 v73, v30, 16, 1
	v_add3_u32 v73, v30, v73, s26
	global_store_short_d16_hi v71, v73, s[38:39]
	v_bfe_u32 v74, v31, 16, 1
	v_add3_u32 v74, v31, v74, s26
	global_store_short_d16_hi v71, v74, s[38:39] offset:2048
	v_bfe_u32 v75, v14, 16, 1
	v_add3_u32 v75, v14, v75, s26
	global_store_short_d16_hi v71, v75, s[38:39] offset:128
	v_bfe_u32 v76, v15, 16, 1
	v_add3_u32 v76, v15, v76, s26
	global_store_short_d16_hi v71, v76, s[38:39] offset:2176
	v_add_u32_e32 v72, 0x1d000, v70
	v_bfe_u32 v77, v32, 16, 1
	v_add3_u32 v77, v32, v77, s26
	global_store_short_d16_hi v72, v77, s[38:39]
	v_bfe_u32 v78, v33, 16, 1
	v_add3_u32 v78, v33, v78, s26
	global_store_short_d16_hi v72, v78, s[38:39] offset:2048
	v_bfe_u32 v79, v16, 16, 1
	v_add3_u32 v79, v16, v79, s26
	global_store_short_d16_hi v72, v79, s[38:39] offset:128
	v_bfe_u32 v80, v17, 16, 1
	v_add3_u32 v80, v17, v80, s26
	global_store_short_d16_hi v72, v80, s[38:39] offset:2176
	s_nop 0
	v_readlane_b32 s38, v252, 2
	v_readlane_b32 s39, v252, 3
	s_load_dword s11, s[38:39], 0x0
	s_waitcnt lgkmcnt(0)
	s_add_i32 s16, s11, s16
	s_cmpk_gt_i32 s16, 0x1ff
	s_cbranch_scc0 .LBB0_88
